# attention K/V tile loads: scalar base + 32-bit lane offset (no per-tile 64-bit VALU address math); plus scalar row-sum, P10 newest-first, P1+P8 4x8 order
# speedup vs baseline: 1.0079x; 1.0015x over previous
; #define LAS __attribute__((address_space(3)))
; __device__ __forceinline__ void attn_unit(const bf16* __restrict__ QB, const bf16* __restrict__ KB, const bf16* __restrict__ VB, bf16* __restrict__ YATT, ...
;     ...
;     const bf16* ksrc[2]; int kdst[2];
; #pragma unroll
;     for (int i = 0; i < 2; ++i) { const int idx = tid + 512 * i, comp = idx >> 9, key = (idx >> 3) & 63, ch = idx & 7; ksrc[i] = Kg + (size_t)key * 512 + comp * 64 + ch * 8; kdst[i] = comp * AK_BYTES + key * AK_STRIDE + ch * 16; }
;     const bf16* vsrc[2]; int vdst[2];
; #pragma unroll
;     for (int i = 0; i < 2; ++i) { const int idx = tid + 512 * i, key = idx >> 4, ch = idx & 15; vsrc[i] = Vg + (size_t)key * 512 + ch * 8; vdst[i] = ((key >> 3) * 4 + (ch >> 2)) * 512 + (key & 7) * 64 + (ch & 3) * 16; }
;     LAS unsigned char* Kl = lds + A_KOFF; LAS unsigned char* Vl = lds + A_VOFF;
;     const int kfo = jc * AK_BYTES + r32 * AK_STRIDE + hi * 16;
;     const int vb = (4 * hi + ((lane & 15) >> 2)) * 64 + ((lane >> 4) & 1) * 32 + (lane & 3) * 8;
;     f32x16 acc[4];
; #pragma unroll
;     for (int e = 0; e < 4; ++e) acc[e] = f32x16{};
;     f32x16 negc = f32x16{};
;     float lrun = 0.f;
;     constexpr float THR = 60.f;
;     u32x4 kreg[2], vreg[2];
;     { const size_t go = (size_t)jstart * 64 * 512; kreg[0] = *(const u32x4*)(ksrc[0] + go); kreg[1] = *(const u32x4*)(ksrc[1] + go); vreg[0] = *(const u32x4*)(vsrc[0] + go); vreg[1] = *(const u32x4*)(vsrc[1] + go); }
;     *(LAS u32x4*)(Kl + kdst[0]) = kreg[0]; *(LAS u32x4*)(Kl + kdst[1]) = kreg[1]; *(LAS u32x4*)(Vl + vdst[0]) = vreg[0]; *(LAS u32x4*)(Vl + vdst[1]) = vreg[1];
;     __syncthreads();
.LBB0_569:
	s_or_b64 exec, exec, s[14:15]
	s_mul_i32 s82, s72, 0x202000
	s_lshl_b64 s[14:15], s[82:83], 1
	s_add_u32 s16, s6, s14
	s_addc_u32 s18, s7, s15
	s_add_u32 s14, s8, s14
	s_addc_u32 s15, s9, s15
	s_lshl_b32 s82, s17, 1
	s_add_u32 s14, s14, s82
	v_bfe_u32 v7, v17, 3, 6
	s_addc_u32 s15, s15, 0
	v_lshlrev_b32_e32 v4, 10, v7
	v_lshlrev_b32_e32 v34, 4, v17
	v_lshl_add_u64 v[2:3], s[14:15], 0, v[4:5]
	v_and_b32_e32 v4, 0x70, v34
	v_lshl_add_u64 v[2:3], v[2:3], 0, v[4:5]
	s_mov_b64 s[14:15], 0xc940000
	v_add_u32_e32 v36, 0x200, v17
	v_lshl_add_u64 v[10:11], v[2:3], 0, s[14:15]
	s_movk_i32 s14, 0x90
	v_ashrrev_i32_e32 v35, 9, v17
	v_ashrrev_i32_e32 v37, 9, v36
	s_add_u32 s16, s16, s82
	v_mad_u32_u24 v7, v7, s14, v4
	v_lshlrev_b32_e32 v2, 6, v35
	v_lshlrev_b32_e32 v8, 6, v37
	v_and_b32_e32 v4, 15, v17
	s_addc_u32 s17, s18, 0
	v_ashrrev_i32_e32 v3, 31, v2
	v_ashrrev_i32_e32 v9, 31, v8
	v_lshlrev_b32_e32 v4, 4, v4
	v_ashrrev_i32_e32 v30, 4, v17
	v_ashrrev_i32_e32 v32, 4, v36
	v_lshl_add_u64 v[20:21], v[2:3], 1, v[10:11]
	v_lshl_add_u64 v[22:23], v[8:9], 1, v[10:11]
	v_lshl_add_u64 v[10:11], s[16:17], 0, v[4:5]
	s_mov_b64 s[14:15], 0xe980000
	v_ashrrev_i32_e32 v31, 31, v30
	v_ashrrev_i32_e32 v33, 31, v32
	v_lshl_add_u64 v[14:15], v[10:11], 0, s[14:15]
	v_lshlrev_b64 v[10:11], 10, v[30:31]
	v_lshlrev_b64 v[12:13], 10, v[32:33]
	v_mov_b32_e32 v179, v5
	v_lshl_add_u64 v[24:25], v[14:15], 0, v[10:11]
	v_lshl_add_u64 v[26:27], v[14:15], 0, v[12:13]
	v_lshlrev_b64 v[14:15], 16, v[178:179]
	v_lshl_add_u64 v[20:21], v[20:21], 0, v[14:15]
	v_lshl_add_u64 v[22:23], v[22:23], 0, v[14:15]
	global_load_dwordx4 v[158:161], v[20:21], off
	global_load_dwordx4 v[162:165], v[22:23], off
	v_lshl_add_u64 v[20:21], v[24:25], 0, v[14:15]
	v_lshl_add_u64 v[22:23], v[26:27], 0, v[14:15]
	global_load_dwordx4 v[166:169], v[20:21], off
	global_load_dwordx4 v[170:173], v[22:23], off
	v_bfe_u32 v31, v17, 2, 2
	v_lshrrev_b32_e32 v33, 5, v17
	v_and_or_b32 v33, v33, s77, v31
	v_lshlrev_b32_e32 v30, 6, v30
	v_lshrrev_b32_e32 v36, 5, v36
	v_and_b32_e32 v34, 48, v34
	v_lshlrev_b32_e32 v33, 9, v33
	v_and_b32_e32 v30, 0x1c0, v30
	v_and_or_b32 v31, v36, s77, v31
	v_lshlrev_b32_e32 v32, 6, v32
	s_load_dwordx2 s[90:91], s[12:13], 0xa0
	s_load_dwordx2 s[88:89], s[10:11], 0xf0
	v_or3_b32 v196, v33, v30, v34
	v_lshlrev_b32_e32 v30, 9, v31
	v_and_b32_e32 v31, 0x1c0, v32
	v_mad_i32_i24 v198, v35, s76, v7
	v_mad_i32_i24 v199, v37, s76, v7
	v_or3_b32 v197, v30, v31, v34
	v_add_u32_e32 v7, 0, v198
	v_add_u32_e32 v32, 0, v199
	v_add_u32_e32 v30, 0, v196
	v_add_u32_e32 v31, 0, v197
	v_mov_b32_e32 v33, v5
	v_lshlrev_b32_e32 v179, 2, v18
	v_mov_b32_e32 v18, v5
	v_mov_b32_e32 v19, v5
	v_mov_b32_e32 v20, v5
	v_mov_b32_e32 v21, v5
	v_mov_b32_e32 v22, v5
	v_mov_b32_e32 v23, v5
	v_mov_b32_e32 v24, v5
	v_mov_b32_e32 v25, v5
	v_mov_b32_e32 v26, v5
	v_mov_b32_e32 v27, v5
	v_mov_b32_e32 v28, v5
	v_mov_b32_e32 v29, v5
	s_add_i32 s10, s80, 31
	v_cmp_gt_u32_e32 vcc, s39, v178
	s_ashr_i32 s73, s10, 6
	s_waitcnt vmcnt(3)
	ds_write_b128 v7, v[158:161]
	s_waitcnt vmcnt(2)
	ds_write_b128 v32, v[162:165]
	s_waitcnt vmcnt(1)
	ds_write_b128 v30, v[166:169] offset:36864
	s_waitcnt vmcnt(0)
	ds_write_b128 v31, v[170:173] offset:36864
	v_mov_b32_e32 v32, v5
	v_mov_b32_e32 v30, v5
	v_mov_b32_e32 v31, v5
	v_mov_b64_e32 v[48:49], v[32:33]
	v_mov_b64_e32 v[64:65], v[32:33]
	v_mov_b64_e32 v[80:81], v[32:33]
	v_mov_b64_e32 v[46:47], v[30:31]
	v_mov_b64_e32 v[44:45], v[28:29]
	v_mov_b64_e32 v[42:43], v[26:27]
	v_mov_b64_e32 v[40:41], v[24:25]
	v_mov_b64_e32 v[38:39], v[22:23]
	v_mov_b64_e32 v[36:37], v[20:21]
	v_mov_b64_e32 v[34:35], v[18:19]
	v_mov_b64_e32 v[62:63], v[30:31]
	v_mov_b64_e32 v[60:61], v[28:29]
	v_mov_b64_e32 v[58:59], v[26:27]
	v_mov_b64_e32 v[56:57], v[24:25]
	v_mov_b64_e32 v[54:55], v[22:23]
	v_mov_b64_e32 v[52:53], v[20:21]
	v_mov_b64_e32 v[50:51], v[18:19]
	v_mov_b64_e32 v[78:79], v[30:31]
	v_mov_b64_e32 v[76:77], v[28:29]
	v_mov_b64_e32 v[74:75], v[26:27]
	v_mov_b64_e32 v[72:73], v[24:25]
	v_mov_b64_e32 v[70:71], v[22:23]
	v_mov_b64_e32 v[68:69], v[20:21]
	v_mov_b64_e32 v[66:67], v[18:19]
	s_waitcnt lgkmcnt(0)
	s_barrier
	s_and_saveexec_b64 s[92:93], vcc
	s_cbranch_execz .LBB0_583
; __device__ __forceinline__ void attn_unit(const bf16* __restrict__ QB, const bf16* __restrict__ KB, const bf16* __restrict__ VB, bf16* __restrict__ YATT, ...
;     ...
;     const bf16* ksrc[2]; int kdst[2];
; #pragma unroll
;     for (int i = 0; i < 2; ++i) { const int idx = tid + 512 * i, comp = idx >> 9, key = (idx >> 3) & 63, ch = idx & 7; ksrc[i] = Kg + (size_t)key * 512 + comp * 64 + ch * 8; kdst[i] = comp * AK_BYTES + key * AK_STRIDE + ch * 16; }
;     const bf16* vsrc[2]; int vdst[2];
; #pragma unroll
;     for (int i = 0; i < 2; ++i) { const int idx = tid + 512 * i, key = idx >> 4, ch = idx & 15; vsrc[i] = Vg + (size_t)key * 512 + ch * 8; vdst[i] = ((key >> 3) * 4 + (ch >> 2)) * 512 + (key & 7) * 64 + (ch & 3) * 16; }
;     ...
;     for (int j = jstart; j < NT; ++j) {
;         const int cur = (j - jstart) & 1;
;         if (j + 1 < NT) { const size_t go = (size_t)(j + 1) * 64 * 512; kreg[0] = *(const u32x4*)(ksrc[0] + go); kreg[1] = *(const u32x4*)(ksrc[1] + go); vreg[0] = *(const u32x4*)(vsrc[0] + go); vreg[1] = *(const u32x4*)(vsrc[1] + go); }
	v_lshrrev_b32_e32 v18, 2, v17
	s_mul_i32 s10, s38, 0x2400
	v_mul_u32_u24_e32 v7, 0x90, v83
	v_and_or_b32 v18, v18, 3, v179
	v_lshlrev_b32_e32 v19, 1, v17
	v_lshlrev_b32_e32 v20, 3, v17
	s_add_i32 s10, s10, 0
	v_and_b32_e32 v19, 32, v19
	v_and_b32_e32 v20, 24, v20
	v_add3_u32 v200, s10, v7, v6
	v_lshl_add_u32 v6, v18, 6, 0
	v_add3_u32 v201, v6, v19, v20
	v_sub_u32_e32 v6, s80, v16
	v_max_i32_e32 v6, 0, v6
	v_lshrrev_b32_e32 v202, 6, v6
	s_ashr_i32 s10, s80, 6
	v_sub_u32_e32 v6, v82, v179
	v_lshlrev_b32_e32 v7, 6, v178
	v_subrev_u32_e32 v203, s10, v178
	v_sub_u32_e32 v204, v6, v7
	v_or_b32_e32 v205, 63, v7
	v_mad_u64_u32 v[6:7], s[10:11], s72, v188, v[14:15]
	v_lshlrev_b32_e32 v14, 7, v17
	v_and_b32_e32 v14, 0xfc00, v14
	v_mov_b32_e32 v15, v5
	v_lshl_add_u64 v[14:15], v[6:7], 0, v[14:15]
	v_and_b32_e32 v16, 7, v17
	s_add_u32 s8, s8, 0xc950000
	v_lshl_or_b32 v14, v16, 4, v14
	s_addc_u32 s9, s9, 0
	v_lshl_add_u64 v[2:3], v[2:3], 1, v[14:15]
	v_lshl_add_u64 v[180:181], s[8:9], 0, v[2:3]
	v_lshl_add_u64 v[2:3], v[8:9], 1, v[14:15]
	v_lshl_add_u64 v[182:183], s[8:9], 0, v[2:3]
	s_add_u32 s6, s6, 0xe990000
	v_lshl_add_u64 v[2:3], v[6:7], 0, v[10:11]
	s_addc_u32 s7, s7, 0
	v_lshl_add_u64 v[2:3], v[2:3], 0, v[4:5]
	v_lshl_add_u64 v[184:185], s[6:7], 0, v[2:3]
	v_lshl_add_u64 v[2:3], v[6:7], 0, v[12:13]
	v_lshl_add_u64 v[2:3], v[2:3], 0, v[4:5]
	v_mov_b32_e32 v16, v5
	v_mov_b32_e32 v17, v5
	v_lshl_add_u64 v[186:187], s[6:7], 0, v[2:3]
	s_nop 0
	v_readfirstlane_b32 s98, v180
	v_readfirstlane_b32 s99, v181
	v_readfirstlane_b32 s100, v184
	v_readfirstlane_b32 s101, v185
	s_nop 3
	v_subrev_u32_e32 v180, s98, v180
	v_subrev_u32_e32 v182, s98, v182
	v_subrev_u32_e32 v184, s100, v184
	v_subrev_u32_e32 v186, s100, v186
	s_add_u32 s98, s98, s82
	s_addc_u32 s99, s99, s83
	s_add_u32 s100, s100, s82
	s_addc_u32 s101, s101, s83
	v_mov_b32_e32 v2, v5
	v_mov_b32_e32 v3, v5
	v_mov_b32_e32 v4, v5
	v_mov_b32_e32 v6, v5
	v_mov_b32_e32 v7, v5
	v_mov_b32_e32 v8, v5
	v_mov_b32_e32 v9, v5
	v_mov_b32_e32 v10, v5
	v_mov_b32_e32 v11, v5
	v_mov_b32_e32 v12, v5
	v_mov_b32_e32 v13, v5
	v_mov_b32_e32 v14, v5
	v_mov_b32_e32 v15, v5
	v_mov_b64_e32 v[80:81], v[16:17]
	v_mov_b64_e32 v[64:65], v[16:17]
	v_mov_b64_e32 v[48:49], v[16:17]
	v_mov_b64_e32 v[32:33], v[16:17]
	v_mov_b64_e32 v[96:97], v[16:17]
	s_mov_b32 s81, 0
	v_sub_u32_e32 v206, v202, v178
	v_mov_b32_e32 v207, 0
	s_mov_b64 s[94:95], 0
	v_mov_b64_e32 v[78:79], v[14:15]
	v_mov_b64_e32 v[76:77], v[12:13]
	v_mov_b64_e32 v[74:75], v[10:11]
	v_mov_b64_e32 v[72:73], v[8:9]
	v_mov_b64_e32 v[70:71], v[6:7]
	v_mov_b64_e32 v[68:69], v[4:5]
	v_mov_b64_e32 v[66:67], v[2:3]
	v_mov_b64_e32 v[62:63], v[14:15]
	v_mov_b64_e32 v[60:61], v[12:13]
	v_mov_b64_e32 v[58:59], v[10:11]
	v_mov_b64_e32 v[56:57], v[8:9]
	v_mov_b64_e32 v[54:55], v[6:7]
	v_mov_b64_e32 v[52:53], v[4:5]
	v_mov_b64_e32 v[50:51], v[2:3]
	v_mov_b64_e32 v[46:47], v[14:15]
	v_mov_b64_e32 v[44:45], v[12:13]
	v_mov_b64_e32 v[42:43], v[10:11]
	v_mov_b64_e32 v[40:41], v[8:9]
	v_mov_b64_e32 v[38:39], v[6:7]
	v_mov_b64_e32 v[36:37], v[4:5]
	v_mov_b64_e32 v[34:35], v[2:3]
	v_mov_b64_e32 v[30:31], v[14:15]
	v_mov_b64_e32 v[28:29], v[12:13]
	v_mov_b64_e32 v[26:27], v[10:11]
	v_mov_b64_e32 v[24:25], v[8:9]
	v_mov_b64_e32 v[22:23], v[6:7]
	v_mov_b64_e32 v[20:21], v[4:5]
	v_mov_b64_e32 v[18:19], v[2:3]
	v_mov_b64_e32 v[94:95], v[14:15]
	v_mov_b64_e32 v[92:93], v[12:13]
	v_mov_b64_e32 v[90:91], v[10:11]
	v_mov_b64_e32 v[88:89], v[8:9]
	v_mov_b64_e32 v[86:87], v[6:7]
	v_mov_b64_e32 v[84:85], v[4:5]
	v_mov_b64_e32 v[82:83], v[2:3]
	s_branch .LBB0_572
.LBB0_571:
	s_or_b64 exec, exec, s[8:9]
	s_add_i32 s81, s81, 1
	v_add_u32_e32 v2, s81, v178
	v_cmp_le_u32_e32 vcc, s39, v2
	v_subrev_u32_e32 v204, 64, v204
	v_add_u32_e32 v205, 64, v205
	s_add_u32 s98, s98, 0x10000
	s_addc_u32 s99, s99, 0
	s_add_u32 s100, s100, 0x10000
	s_addc_u32 s101, s101, 0
	s_or_b64 s[94:95], vcc, s[94:95]
	s_waitcnt lgkmcnt(0)
	s_barrier
	s_andn2_b64 exec, exec, s[94:95]
	s_cbranch_execz .LBB0_582
.LBB0_572:
	v_add_u32_e32 v2, s81, v178
	v_add_u32_e32 v3, 1, v2
	v_cmp_gt_u32_e64 s[6:7], s39, v3
	s_and_saveexec_b64 s[8:9], s[6:7]
	s_cbranch_execz .LBB0_574
	global_load_dwordx4 v[158:161], v180, s[98:99]
	global_load_dwordx4 v[162:165], v182, s[98:99]
	global_load_dwordx4 v[166:169], v184, s[100:101]
	global_load_dwordx4 v[170:173], v186, s[100:101]

; __global__ void __launch_bounds__(NWAVES * 64, 2) hybrid_fwd(Params P) {
	.amdhsa_kernel _Z10hybrid_fwd6Params
		.amdhsa_group_segment_fixed_size 0
		.amdhsa_private_segment_fixed_size 0
		.amdhsa_kernarg_size 512
		.amdhsa_user_sgpr_count 2
		.amdhsa_user_sgpr_dispatch_ptr 0
		.amdhsa_user_sgpr_queue_ptr 0
		.amdhsa_user_sgpr_kernarg_segment_ptr 1
		.amdhsa_user_sgpr_dispatch_id 0
		.amdhsa_user_sgpr_kernarg_preload_length 0
		.amdhsa_user_sgpr_kernarg_preload_offset 0
		.amdhsa_user_sgpr_private_segment_size 0
		.amdhsa_uses_dynamic_stack 0
		.amdhsa_enable_private_segment 0
		.amdhsa_system_sgpr_workgroup_id_x 1
		.amdhsa_system_sgpr_workgroup_id_y 0
		.amdhsa_system_sgpr_workgroup_id_z 0
		.amdhsa_system_sgpr_workgroup_info 0
		.amdhsa_system_vgpr_workitem_id 2
		.amdhsa_next_free_vgpr 241
		.amdhsa_next_free_sgpr 102
		.amdhsa_accum_offset 244
		.amdhsa_reserve_vcc 1
		.amdhsa_float_round_mode_32 0
		.amdhsa_float_round_mode_16_64 0
		.amdhsa_float_denorm_mode_32 3
		.amdhsa_float_denorm_mode_16_64 3
		.amdhsa_dx10_clamp 1
		.amdhsa_ieee_mode 1
		.amdhsa_fp16_overflow 0
		.amdhsa_tg_split 0
		.amdhsa_exception_fp_ieee_invalid_op 0
		.amdhsa_exception_fp_denorm_src 0
		.amdhsa_exception_fp_ieee_div_zero 0
		.amdhsa_exception_fp_ieee_overflow 0
		.amdhsa_exception_fp_ieee_underflow 0
		.amdhsa_exception_fp_ieee_inexact 0
		.amdhsa_exception_int_div_zero 0
	.end_amdhsa_kernel

; __global__ void __launch_bounds__(NWAVES * 64, 2) hybrid_fwd(Params P) {
amdhsa.kernels:
  - .agpr_count:     0
    .args:
      - .offset:         0
        .size:           256
        .value_kind:     by_value
      - .offset:         256
        .size:           4
        .value_kind:     hidden_block_count_x
      - .offset:         260
        .size:           4
        .value_kind:     hidden_block_count_y
      - .offset:         264
        .size:           4
        .value_kind:     hidden_block_count_z
      - .offset:         268
        .size:           2
        .value_kind:     hidden_group_size_x
      - .offset:         270
        .size:           2
        .value_kind:     hidden_group_size_y
      - .offset:         272
        .size:           2
        .value_kind:     hidden_group_size_z
      - .offset:         274
        .size:           2
        .value_kind:     hidden_remainder_x
      - .offset:         276
        .size:           2
        .value_kind:     hidden_remainder_y
      - .offset:         278
        .size:           2
        .value_kind:     hidden_remainder_z
      - .offset:         296
        .size:           8
        .value_kind:     hidden_global_offset_x
      - .offset:         304
        .size:           8
        .value_kind:     hidden_global_offset_y
      - .offset:         312
        .size:           8
        .value_kind:     hidden_global_offset_z
      - .offset:         320
        .size:           2
        .value_kind:     hidden_grid_dims
      - .offset:         344
        .size:           8
        .value_kind:     hidden_multigrid_sync_arg
      - .offset:         376
        .size:           4
        .value_kind:     hidden_dynamic_lds_size
    .group_segment_fixed_size: 0
    .kernarg_segment_align: 8
    .kernarg_segment_size: 512
    .language:       OpenCL C
    .language_version:
      - 2
      - 0
    .max_flat_workgroup_size: 512
    .name:           _Z10hybrid_fwd6Params
    .private_segment_fixed_size: 0
    .sgpr_count:     108
    .sgpr_spill_count: 19
    .symbol:         _Z10hybrid_fwd6Params.kd
    .uniform_work_group_size: 1
    .uses_dynamic_stack: false
    .vgpr_count:     241
    .vgpr_spill_count: 0
    .wavefront_size: 64
